# baseline (speedup 1.0000x reference)
; #define LAS __attribute__((address_space(3)))
; __device__ __forceinline__ s16x4 vtr(const LAS char* p) { return __builtin_bit_cast(s16x4, __builtin_amdgcn_ds_read_tr16_b64_v4i16((LAS v4i16_t*)p)); }
; template <int DQK>
; __device__ __forceinline__ void attn_unit64(LAS char* lds, const bf16x8 (&qa)[DQK / 16], const bf16x8 (&qb)[DQK / 16],
;                                             const bf16_t* Kg, int ldk, const bf16_t* Vg, int ldv, int t0, int t1, bf16_t* Oga, int ogb_off) {
;     ...
;         for (int kv = 0; kv < 2; ++kv) {
;             __builtin_amdgcn_iglp_opt(0);
;             f32x16 sa, sb;
; #pragma unroll
;             for (int i = 0; i < 16; ++i) { sa[i] = 0.f; sb[i] = 0.f; }
; #pragma unroll
;             for (int ds = 0; ds < DQK / 16; ++ds) {
;                 const bf16x8 kf = *(const LAS bf16x8*)(kb + kv * 32 * KP + ds * 32);
;                 sa = __builtin_amdgcn_mfma_f32_32x32x16_bf16(kf, qa[ds], sa, 0, 0, 0);
;                 sb = __builtin_amdgcn_mfma_f32_32x32x16_bf16(kf, qb[ds], sb, 0, 0, 0);
;             }
; #pragma unroll
;             for (int i = 0; i < 16; i += 2) { sa[i] = __builtin_amdgcn_exp2f(sa[i]); sa[i + 1] = __builtin_amdgcn_exp2f(sa[i + 1]); la0 += sa[i]; la1 += sa[i + 1];
;                                                sb[i] = __builtin_amdgcn_exp2f(sb[i]); sb[i + 1] = __builtin_amdgcn_exp2f(sb[i + 1]); lb0 += sb[i]; lb1 += sb[i + 1]; }
;             bf16x8 pa[2], pb[2]; pa[0] = pack8(sa, 0); pa[1] = pack8(sa, 1); pb[0] = pack8(sb, 0); pb[1] = pack8(sb, 1);
; #pragma unroll
;             for (int s2 = 0; s2 < 2; ++s2) {
;                 const int s = 2 * kv + s2;
;                 const s16x4 a0 = vtr(vb + (16 * s) * 64), a1 = vtr(vb + (16 * s + 8) * 64), c0 = vtr(vb + 4096 + (16 * s) * 64), c1 = vtr(vb + 4096 + (16 * s + 8) * 64);
;                 const bf16x8 va = (bf16x8){a0[0], a0[1], a0[2], a0[3], a1[0], a1[1], a1[2], a1[3]}, vc = (bf16x8){c0[0], c0[1], c0[2], c0[3], c1[0], c1[1], c1[2], c1[3]};
;                 oa0 = __builtin_amdgcn_mfma_f32_32x32x16_bf16(va, pa[s2], oa0, 0, 0, 0);
;                 oa1 = __builtin_amdgcn_mfma_f32_32x32x16_bf16(vc, pa[s2], oa1, 0, 0, 0);
;                 ob0 = __builtin_amdgcn_mfma_f32_32x32x16_bf16(va, pb[s2], ob0, 0, 0, 0);
;                 ob1 = __builtin_amdgcn_mfma_f32_32x32x16_bf16(vc, pb[s2], ob1, 0, 0, 0);
;             }
.Lp11_g1_pro:
	s_mov_b32 s24, 0x2000
	s_mov_b32 s25, 0
	v_lshl_add_u64 v[180:181], v[168:169], 0, s[24:25]
	global_load_dwordx4 v[104:107], v[180:181], off
	v_mov_b32_e32 v240, v238
	v_add_u32_e32 v241, s99, v238
	v_mov_b32_e32 v242, v239
	v_add_u32_e32 v243, s99, v159
	v_add_u32_e32 v244, s99, v212
	v_add_u32_e32 v245, s99, v179
	v_mov_b32_e32 v64, 0xf149f2ca
	v_mov_b32_e32 v65, v64
	v_mov_b32_e32 v66, v64
	v_mov_b32_e32 v67, v64
	v_mov_b32_e32 v68, v64
	v_mov_b32_e32 v69, v64
	v_mov_b32_e32 v70, v64
	v_mov_b32_e32 v71, v64
	v_mov_b32_e32 v72, v64
	v_mov_b32_e32 v73, v64
	v_mov_b32_e32 v74, v64
	v_mov_b32_e32 v75, v64
	v_mov_b32_e32 v76, v64
	v_mov_b32_e32 v77, v64
	v_mov_b32_e32 v78, v64
	v_mov_b32_e32 v79, v64
	v_mov_b32_e32 v214, 0
	v_mov_b32_e32 v215, 0
	v_mov_b32_e32 v216, 0
	v_mov_b32_e32 v217, 0
	v_mov_b32_e32 v218, 0
	v_mov_b32_e32 v219, 0
	v_mov_b32_e32 v220, 0
	v_mov_b32_e32 v221, 0
	v_mov_b32_e32 v248, 0
	v_mov_b32_e32 v249, 0
	v_mov_b32_e32 v250, 0
	v_mov_b32_e32 v251, 0
	v_mov_b32_e32 v252, 0
	v_mov_b32_e32 v253, 0
	v_mov_b32_e32 v254, 0
	v_mov_b32_e32 v255, 0
	s_cmp_eq_u64 s[0:1], 0
	s_cbranch_scc0 .Lp11_noprio
	s_setprio 1
.Lp11_noprio:
.Lp11_loop:
	s_waitcnt lgkmcnt(0)
	v_mfma_f32_32x32x16_bf16 v[80:95], v[182:185], v[128:131], 0
	v_exp_f32_e32 v64, v64
	v_exp_f32_e32 v65, v65
	v_exp_f32_e32 v66, v66
	v_exp_f32_e32 v67, v67
	v_mfma_f32_32x32x16_bf16 v[80:95], v[186:189], v[124:127], v[80:95]
	v_exp_f32_e32 v68, v68
	v_exp_f32_e32 v69, v69
	v_cvt_pk_bf16_f32 v230, v64, v65
	v_cvt_pk_bf16_f32 v231, v66, v67
	v_mfma_f32_32x32x16_bf16 v[80:95], v[190:193], v[120:123], v[80:95]
	v_exp_f32_e32 v70, v70
	v_exp_f32_e32 v71, v71
	v_exp_f32_e32 v72, v72
	v_cvt_pk_bf16_f32 v232, v68, v69
	v_mfma_f32_32x32x16_bf16 v[80:95], v[194:197], v[116:119], v[80:95]
	v_exp_f32_e32 v73, v73
	v_exp_f32_e32 v74, v74
	v_cvt_pk_bf16_f32 v233, v70, v71
	v_exp_f32_e32 v75, v75
	v_mfma_f32_32x32x16_bf16 v[80:95], v[198:201], v[108:111], v[80:95]
	v_exp_f32_e32 v76, v76
	v_exp_f32_e32 v77, v77
	v_cvt_pk_bf16_f32 v234, v72, v73
	v_cvt_pk_bf16_f32 v235, v74, v75
	v_mfma_f32_32x32x16_bf16 v[80:95], v[202:205], v[112:115], v[80:95]
	v_exp_f32_e32 v78, v78
	v_exp_f32_e32 v79, v79
	v_cvt_pk_bf16_f32 v236, v76, v77
	v_cvt_pk_bf16_f32 v237, v78, v79
	v_mfma_f32_32x32x16_bf16 v[16:31], v[248:251], v[230:233], v[16:31]
	ds_read_b64_tr_b16 v[248:249], v242 offset:13312
	ds_read_b64_tr_b16 v[250:251], v242 offset:13824
	v_add_f32_e32 v172, v172, v64
	v_add_f32_e32 v173, v173, v65
	v_add_f32_e32 v172, v172, v66
	v_add_f32_e32 v173, v173, v67
	v_mfma_f32_32x32x16_bf16 v[0:15], v[252:255], v[230:233], v[0:15]
	ds_read_b64_tr_b16 v[252:253], v242 offset:17408
	ds_read_b64_tr_b16 v[254:255], v242 offset:17920
	v_add_f32_e32 v172, v172, v68
	v_add_f32_e32 v173, v173, v69
	v_add_f32_e32 v172, v172, v70
	v_add_f32_e32 v173, v173, v71
	v_mfma_f32_32x32x16_bf16 v[16:31], v[214:217], v[234:237], v[16:31]
	ds_read_b64_tr_b16 v[214:215], v242 offset:14336
	ds_read_b64_tr_b16 v[216:217], v242 offset:14848
	v_add_f32_e32 v172, v172, v72
	v_add_f32_e32 v173, v173, v73
	v_add_f32_e32 v172, v172, v74
	v_add_f32_e32 v173, v173, v75
	v_mfma_f32_32x32x16_bf16 v[0:15], v[218:221], v[234:237], v[0:15]
	ds_read_b64_tr_b16 v[218:219], v242 offset:18432
	ds_read_b64_tr_b16 v[220:221], v242 offset:18944
	v_add_f32_e32 v172, v172, v76
	v_add_f32_e32 v173, v173, v77
	v_add_f32_e32 v172, v172, v78
	v_add_f32_e32 v173, v173, v79
	v_mfma_f32_32x32x16_bf16 v[64:79], v[182:185], v[132:135], 0
	ds_read_b128 v[182:185], v240 offset:6656
	v_exp_f32_e32 v80, v80
	v_exp_f32_e32 v81, v81
	v_exp_f32_e32 v82, v82
	v_exp_f32_e32 v83, v83
	v_mfma_f32_32x32x16_bf16 v[64:79], v[186:189], v[136:139], v[64:79]
	ds_read_b128 v[186:189], v240 offset:6688
	v_exp_f32_e32 v84, v84
	v_exp_f32_e32 v85, v85
	v_cvt_pk_bf16_f32 v222, v80, v81
	v_cvt_pk_bf16_f32 v223, v82, v83
	v_mfma_f32_32x32x16_bf16 v[64:79], v[190:193], v[140:143], v[64:79]
	ds_read_b128 v[190:193], v240 offset:6720
	v_exp_f32_e32 v86, v86
	v_exp_f32_e32 v87, v87
	v_exp_f32_e32 v88, v88
	v_cvt_pk_bf16_f32 v224, v84, v85
	v_mfma_f32_32x32x16_bf16 v[64:79], v[194:197], v[144:147], v[64:79]
	ds_read_b128 v[194:197], v240 offset:6752
	v_exp_f32_e32 v89, v89
	v_exp_f32_e32 v90, v90
	v_cvt_pk_bf16_f32 v225, v86, v87
	v_exp_f32_e32 v91, v91
	v_mfma_f32_32x32x16_bf16 v[64:79], v[198:201], v[148:151], v[64:79]
	ds_read_b128 v[198:201], v240 offset:6784
	v_exp_f32_e32 v92, v92
	v_exp_f32_e32 v93, v93
	v_cvt_pk_bf16_f32 v226, v88, v89
	v_cvt_pk_bf16_f32 v227, v90, v91
	v_mfma_f32_32x32x16_bf16 v[64:79], v[202:205], v[152:155], v[64:79]
	ds_read_b128 v[202:205], v240 offset:6816
	v_exp_f32_e32 v94, v94
	v_exp_f32_e32 v95, v95
	v_cvt_pk_bf16_f32 v228, v92, v93
	v_cvt_pk_bf16_f32 v229, v94, v95
	s_waitcnt lgkmcnt(6)
	v_mfma_f32_32x32x16_bf16 v[32:47], v[248:251], v[222:225], v[32:47]
	v_add_f32_e32 v170, v170, v80
	v_add_f32_e32 v171, v171, v81
	v_add_f32_e32 v170, v170, v82
	v_add_f32_e32 v171, v171, v83
	s_waitcnt vmcnt(0)
	ds_write_b128 v243, v[96:99]
	s_cmp_eq_u64 s[0:1], 0
	v_mfma_f32_32x32x16_bf16 v[48:63], v[252:255], v[222:225], v[48:63]
	v_add_f32_e32 v170, v170, v84
	v_add_f32_e32 v171, v171, v85
	v_add_f32_e32 v170, v170, v86
	v_add_f32_e32 v171, v171, v87
	s_cbranch_scc1 .Lp11_w1_a
	ds_write_b128 v244, v[100:103]

; template <int DQK>
; __device__ __forceinline__ void attn_unit64(LAS char* lds, const bf16x8 (&qa)[DQK / 16], const bf16x8 (&qb)[DQK / 16],
;                                             const bf16_t* Kg, int ldk, const bf16_t* Vg, int ldv, int t0, int t1, bf16_t* Oga, int ogb_off) {
;     ...
;         for (int kv = 0; kv < 2; ++kv) {
;             __builtin_amdgcn_iglp_opt(0);
;             f32x16 sa, sb;
; #pragma unroll
;             for (int i = 0; i < 16; ++i) { sa[i] = 0.f; sb[i] = 0.f; }
; #pragma unroll
;             for (int ds = 0; ds < DQK / 16; ++ds) {
;                 const bf16x8 kf = *(const LAS bf16x8*)(kb + kv * 32 * KP + ds * 32);
;                 sa = __builtin_amdgcn_mfma_f32_32x32x16_bf16(kf, qa[ds], sa, 0, 0, 0);
;                 sb = __builtin_amdgcn_mfma_f32_32x32x16_bf16(kf, qb[ds], sb, 0, 0, 0);
;             }
; #pragma unroll
;             for (int i = 0; i < 16; i += 2) { sa[i] = __builtin_amdgcn_exp2f(sa[i]); sa[i + 1] = __builtin_amdgcn_exp2f(sa[i + 1]); la0 += sa[i]; la1 += sa[i + 1];
;                                                sb[i] = __builtin_amdgcn_exp2f(sb[i]); sb[i + 1] = __builtin_amdgcn_exp2f(sb[i + 1]); lb0 += sb[i]; lb1 += sb[i + 1]; }
;             bf16x8 pa[2], pb[2]; pa[0] = pack8(sa, 0); pa[1] = pack8(sa, 1); pb[0] = pack8(sb, 0); pb[1] = pack8(sb, 1);
; #pragma unroll
;             for (int s2 = 0; s2 < 2; ++s2) {
;                 const int s = 2 * kv + s2;
;                 const s16x4 a0 = vtr(vb + (16 * s) * 64), a1 = vtr(vb + (16 * s + 8) * 64), c0 = vtr(vb + 4096 + (16 * s) * 64), c1 = vtr(vb + 4096 + (16 * s + 8) * 64);
;                 const bf16x8 va = (bf16x8){a0[0], a0[1], a0[2], a0[3], a1[0], a1[1], a1[2], a1[3]}, vc = (bf16x8){c0[0], c0[1], c0[2], c0[3], c1[0], c1[1], c1[2], c1[3]};
;                 oa0 = __builtin_amdgcn_mfma_f32_32x32x16_bf16(va, pa[s2], oa0, 0, 0, 0);
;                 oa1 = __builtin_amdgcn_mfma_f32_32x32x16_bf16(vc, pa[s2], oa1, 0, 0, 0);
;                 ob0 = __builtin_amdgcn_mfma_f32_32x32x16_bf16(va, pb[s2], ob0, 0, 0, 0);
;                 ob1 = __builtin_amdgcn_mfma_f32_32x32x16_bf16(vc, pb[s2], ob1, 0, 0, 0);
;             }
;         }
;         if (more) { const unsigned bo = (cur ^ 1) * BUF; *(LAS u32x4*)(lds + bo + kdst0) = kreg0; if (k2) *(LAS u32x4*)(lds + bo + kdst1) = kreg1; *(LAS u32x4*)(lds + bo + vdst) = vreg; }
;         __syncthreads();
.Lp11_g1_a:
	global_load_dwordx4 v[104:107], v[180:181], off
	s_waitcnt lgkmcnt(2)
	v_mfma_f32_32x32x16_bf16 v[80:95], v[182:185], v[128:131], 0
	v_exp_f32_e32 v64, v64
	v_exp_f32_e32 v65, v65
	v_exp_f32_e32 v66, v66
	v_exp_f32_e32 v67, v67
	v_mfma_f32_32x32x16_bf16 v[80:95], v[186:189], v[124:127], v[80:95]
	v_exp_f32_e32 v68, v68
	v_exp_f32_e32 v69, v69
	v_cvt_pk_bf16_f32 v230, v64, v65
	v_cvt_pk_bf16_f32 v231, v66, v67
	v_mfma_f32_32x32x16_bf16 v[80:95], v[190:193], v[120:123], v[80:95]
	v_exp_f32_e32 v70, v70
	v_exp_f32_e32 v71, v71
	v_exp_f32_e32 v72, v72
	v_cvt_pk_bf16_f32 v232, v68, v69
	v_mfma_f32_32x32x16_bf16 v[80:95], v[194:197], v[116:119], v[80:95]
	v_exp_f32_e32 v73, v73
	v_exp_f32_e32 v74, v74
	v_cvt_pk_bf16_f32 v233, v70, v71
	v_exp_f32_e32 v75, v75
	v_mfma_f32_32x32x16_bf16 v[80:95], v[198:201], v[108:111], v[80:95]
	v_exp_f32_e32 v76, v76
	v_exp_f32_e32 v77, v77
	v_cvt_pk_bf16_f32 v234, v72, v73
	v_cvt_pk_bf16_f32 v235, v74, v75
	v_mfma_f32_32x32x16_bf16 v[80:95], v[202:205], v[112:115], v[80:95]
	v_exp_f32_e32 v78, v78
	v_exp_f32_e32 v79, v79
	v_cvt_pk_bf16_f32 v236, v76, v77
	v_cvt_pk_bf16_f32 v237, v78, v79
	v_mfma_f32_32x32x16_bf16 v[16:31], v[248:251], v[230:233], v[16:31]
	ds_read_b64_tr_b16 v[248:249], v242 offset:15360
	ds_read_b64_tr_b16 v[250:251], v242 offset:15872
	v_add_f32_e32 v172, v172, v64
	v_add_f32_e32 v173, v173, v65
	v_add_f32_e32 v172, v172, v66
	v_add_f32_e32 v173, v173, v67
	v_mfma_f32_32x32x16_bf16 v[0:15], v[252:255], v[230:233], v[0:15]
	ds_read_b64_tr_b16 v[252:253], v242 offset:19456
	ds_read_b64_tr_b16 v[254:255], v242 offset:19968
	v_add_f32_e32 v172, v172, v68
	v_add_f32_e32 v173, v173, v69
	v_add_f32_e32 v172, v172, v70
	v_add_f32_e32 v173, v173, v71
	v_mfma_f32_32x32x16_bf16 v[16:31], v[214:217], v[234:237], v[16:31]
	ds_read_b64_tr_b16 v[214:215], v242 offset:16384
	ds_read_b64_tr_b16 v[216:217], v242 offset:16896
	v_add_f32_e32 v172, v172, v72
	v_add_f32_e32 v173, v173, v73
	v_add_f32_e32 v172, v172, v74
	v_add_f32_e32 v173, v173, v75
	v_mfma_f32_32x32x16_bf16 v[0:15], v[218:221], v[234:237], v[0:15]
	ds_read_b64_tr_b16 v[218:219], v242 offset:20480
	ds_read_b64_tr_b16 v[220:221], v242 offset:20992
	v_add_f32_e32 v172, v172, v76
	v_add_f32_e32 v173, v173, v77
	v_add_f32_e32 v172, v172, v78
	v_add_f32_e32 v173, v173, v79
	s_waitcnt lgkmcnt(8)
	s_barrier
	v_mfma_f32_32x32x16_bf16 v[64:79], v[182:185], v[132:135], 0
	ds_read_b128 v[182:185], v241
	v_exp_f32_e32 v80, v80
	v_exp_f32_e32 v81, v81
	v_exp_f32_e32 v82, v82
	v_exp_f32_e32 v83, v83
	v_mfma_f32_32x32x16_bf16 v[64:79], v[186:189], v[136:139], v[64:79]
	ds_read_b128 v[186:189], v241 offset:32
	v_exp_f32_e32 v84, v84
	v_exp_f32_e32 v85, v85
	v_cvt_pk_bf16_f32 v222, v80, v81
	v_cvt_pk_bf16_f32 v223, v82, v83
	v_mfma_f32_32x32x16_bf16 v[64:79], v[190:193], v[140:143], v[64:79]
	ds_read_b128 v[190:193], v241 offset:64
	v_exp_f32_e32 v86, v86
	v_exp_f32_e32 v87, v87
	v_exp_f32_e32 v88, v88
	v_cvt_pk_bf16_f32 v224, v84, v85
	v_mfma_f32_32x32x16_bf16 v[64:79], v[194:197], v[144:147], v[64:79]
	ds_read_b128 v[194:197], v241 offset:96
	v_exp_f32_e32 v89, v89
	v_exp_f32_e32 v90, v90
	v_cvt_pk_bf16_f32 v225, v86, v87
	v_exp_f32_e32 v91, v91
	v_mfma_f32_32x32x16_bf16 v[64:79], v[198:201], v[148:151], v[64:79]
	ds_read_b128 v[198:201], v241 offset:128
	v_exp_f32_e32 v92, v92
	v_exp_f32_e32 v93, v93
	v_cvt_pk_bf16_f32 v226, v88, v89
	v_cvt_pk_bf16_f32 v227, v90, v91
	v_mfma_f32_32x32x16_bf16 v[64:79], v[202:205], v[152:155], v[64:79]
	ds_read_b128 v[202:205], v241 offset:160
	v_exp_f32_e32 v94, v94
	v_exp_f32_e32 v95, v95
	v_cvt_pk_bf16_f32 v228, v92, v93
	v_cvt_pk_bf16_f32 v229, v94, v95
	s_waitcnt lgkmcnt(6)
	v_mfma_f32_32x32x16_bf16 v[32:47], v[248:251], v[222:225], v[32:47]
	v_add_f32_e32 v170, v170, v80
	v_add_f32_e32 v171, v171, v81
	v_add_f32_e32 v170, v170, v82
	v_add_f32_e32 v171, v171, v83
	v_mfma_f32_32x32x16_bf16 v[48:63], v[252:255], v[222:225], v[48:63]
	v_add_f32_e32 v170, v170, v84
	v_add_f32_e32 v171, v171, v85
	v_add_f32_e32 v170, v170, v86
	v_add_f32_e32 v171, v171, v87
	s_mov_b32 s20, s98
	s_mov_b32 s98, s99
	s_mov_b32 s99, s100
	s_mov_b32 s100, s20
	v_mfma_f32_32x32x16_bf16 v[32:47], v[214:217], v[226:229], v[32:47]
	v_add_f32_e32 v170, v170, v88
	v_add_f32_e32 v171, v171, v89
	v_add_f32_e32 v170, v170, v90
	v_add_f32_e32 v171, v171, v91
	v_add_u32_e32 v240, s98, v238
	v_add_u32_e32 v241, s99, v238
	v_add_u32_e32 v242, s98, v239
	v_mfma_f32_32x32x16_bf16 v[48:63], v[218:221], v[226:229], v[48:63]
	v_add_f32_e32 v170, v170, v92
	v_add_f32_e32 v171, v171, v93
	v_add_f32_e32 v170, v170, v94
	v_add_f32_e32 v171, v171, v95
	v_add_u32_e32 v243, s99, v159
	v_add_u32_e32 v244, s99, v212
	v_add_u32_e32 v245, s99, v179
	s_add_i32 s4, s4, 1
	s_cmp_lt_u32 s4, s39
	s_cbranch_scc1 .Lp11_loop
	v_exp_f32_e32 v64, v64
	v_exp_f32_e32 v65, v65
	v_exp_f32_e32 v66, v66
	v_exp_f32_e32 v67, v67
	v_exp_f32_e32 v68, v68
	v_exp_f32_e32 v69, v69
	v_cvt_pk_bf16_f32 v230, v64, v65
	v_cvt_pk_bf16_f32 v231, v66, v67
	v_exp_f32_e32 v70, v70
	v_exp_f32_e32 v71, v71
	v_exp_f32_e32 v72, v72
	v_cvt_pk_bf16_f32 v232, v68, v69
	v_exp_f32_e32 v73, v73
	v_exp_f32_e32 v74, v74
	v_cvt_pk_bf16_f32 v233, v70, v71
	v_exp_f32_e32 v75, v75
	v_exp_f32_e32 v76, v76
	v_exp_f32_e32 v77, v77
	v_cvt_pk_bf16_f32 v234, v72, v73
	v_cvt_pk_bf16_f32 v235, v74, v75
	v_exp_f32_e32 v78, v78
	v_exp_f32_e32 v79, v79
	v_cvt_pk_bf16_f32 v236, v76, v77
	v_cvt_pk_bf16_f32 v237, v78, v79
	v_add_f32_e32 v172, v172, v64
	v_add_f32_e32 v173, v173, v65
	v_add_f32_e32 v172, v172, v66
	v_add_f32_e32 v173, v173, v67
	v_add_f32_e32 v172, v172, v68
	v_add_f32_e32 v173, v173, v69
	v_add_f32_e32 v172, v172, v70
	v_add_f32_e32 v173, v173, v71
	v_add_f32_e32 v172, v172, v72
	v_add_f32_e32 v173, v173, v73
	v_add_f32_e32 v172, v172, v74
	v_add_f32_e32 v173, v173, v75
	v_add_f32_e32 v172, v172, v76
	v_add_f32_e32 v173, v173, v77
	v_add_f32_e32 v172, v172, v78
	v_add_f32_e32 v173, v173, v79
	s_nop 1
	v_mfma_f32_32x32x16_bf16 v[16:31], v[248:251], v[230:233], v[16:31]
	v_mfma_f32_32x32x16_bf16 v[0:15], v[252:255], v[230:233], v[0:15]
	v_mfma_f32_32x32x16_bf16 v[16:31], v[214:217], v[234:237], v[16:31]
	v_mfma_f32_32x32x16_bf16 v[0:15], v[218:221], v[234:237], v[0:15]
	s_waitcnt vmcnt(0)
	s_waitcnt lgkmcnt(0)
	s_setprio 0
	s_barrier
	s_branch .LBB0_1115
